# static s_setprio 1 for waves 4-7 during the MoBA/FoX/stick-breaking queues
# baseline (speedup 1.0000x reference)
; #define LAS __attribute__((address_space(3)))
; __global__ void __launch_bounds__(512, 2) mega_fwd(Args a) {
;     ...
;             for (int rep = 0; rep < REP_CD; ++rep) {
;                 LAS int* qw = (LAS int*)(lds + 147200);
;                 for (int sq = 0; sq < 8; ++sq) {
.LBB0_307:
	v_readlane_b32 s2, v254, 44
	s_cmp_lt_u32 s2, 4
	s_cbranch_scc1 .Lprio_skip
	s_setprio 1

; __device__ __forceinline__ unsigned xb_ld(unsigned* p)              { return __hip_atomic_load(p, __ATOMIC_RELAXED, __HIP_MEMORY_SCOPE_AGENT); }
; __device__ __forceinline__ void xcd_barrier_complete(unsigned* bar, unsigned x, unsigned& nloc, unsigned& nx) {
;     const unsigned G = gridDim.x * gridDim.y * gridDim.z;
;     unsigned sum, cnt, mine, sp = 0u;
;     for (;;) {
;         sum = 0u; cnt = 0u; mine = 0u;
; #pragma unroll
;         for (unsigned j = 0; j < 16; ++j) { const unsigned c = xb_ld(&bar[XB_XCNT(j)]); sum += c; cnt += (c > 0u) ? 1u : 0u; mine = (j == x) ? c : mine; }
;         if (sum == G) break;
; __device__ __forceinline__ void xcd_barrier(const XcdBarrier& b) {
;     asm volatile("s_waitcnt vmcnt(0)" ::: "memory");
;     __syncthreads();
;     if (threadIdx.x == 0) {
;         unsigned* bar = b.bar;
;         __builtin_amdgcn_s_waitcnt(0);
;         unsigned nloc = b.st[0], nx = b.st[1];
;         if (nloc == 0u) { xcd_barrier_complete(bar, b.x, nloc, nx); b.st[0] = nloc; b.st[1] = nx; }
.LBB0_453:
	s_setprio 0
	v_readlane_b32 s66, v254, 29
	v_readlane_b32 s67, v254, 30
	s_mov_b64 s[2:3], s[66:67]
	s_getreg_b32 s4, hwreg(HW_REG_XCC_ID, 0, 4)
	s_waitcnt vmcnt(0)
	v_readlane_b32 s70, v254, 33
	v_readlane_b32 s71, v254, 34
	s_barrier
	s_and_saveexec_b64 s[0:1], s[70:71]
	v_readlane_b32 s84, v254, 42
	v_readlane_b32 s65, v254, 28
	v_readlane_b32 s68, v254, 31
	s_mov_b64 s[72:73], 0x20000
	s_mov_b32 s54, 0x100000
	s_mov_b32 s55, 0x120000
	s_mov_b32 s56, 0x140000
	s_mov_b32 s57, 0x160000
	v_readlane_b32 s85, v254, 43
	v_readlane_b32 s69, v254, 32
	s_cbranch_execz .LBB0_505
	v_mov_b32_e32 v0, s79
	s_load_dwordx2 s[2:3], s[2:3], 0x40
	s_waitcnt vmcnt(0) expcnt(0) lgkmcnt(0)
	ds_read_b32 v3, v0
	v_mov_b32_e32 v0, s80
	ds_read_b32 v0, v0
	s_and_b32 s48, s4, 15
	s_waitcnt lgkmcnt(1)
	v_cmp_ne_u32_e32 vcc, 0, v3
	s_cbranch_vccnz .LBB0_469
	s_add_u32 s4, s2, 0xc200
	s_addc_u32 s5, s3, 0
	s_add_u32 s8, s2, 0xc400
	s_addc_u32 s9, s3, 0
	s_add_u32 s10, s2, 0xc500
	s_addc_u32 s11, s3, 0
	s_add_u32 s12, s2, 0xc600
	s_addc_u32 s13, s3, 0
	s_add_u32 s14, s2, 0xc700
	s_addc_u32 s15, s3, 0
	s_add_u32 s16, s2, 0xc800
	s_addc_u32 s17, s3, 0
	s_add_u32 s18, s2, 0xc900
	s_addc_u32 s19, s3, 0
	s_add_u32 s20, s2, 0xca00
	s_addc_u32 s21, s3, 0
	s_add_u32 s22, s2, 0xcb00
	s_addc_u32 s23, s3, 0
	s_add_u32 s24, s2, 0xcc00
	s_addc_u32 s25, s3, 0
	s_add_u32 s26, s2, 0xcd00
	s_addc_u32 s27, s3, 0
	s_add_u32 s28, s2, 0xce00
	s_addc_u32 s29, s3, 0
	s_add_u32 s30, s2, 0xcf00
	s_addc_u32 s31, s3, 0
	s_add_u32 s34, s2, 0xd000
	s_addc_u32 s35, s3, 0
	s_add_u32 s36, s2, 0xd100
	s_addc_u32 s37, s3, 0
	s_add_u32 s38, s2, 0xd200
	s_addc_u32 s39, s3, 0
	s_add_u32 s40, s2, 0xd300
	s_addc_u32 s41, s3, 0
	s_mov_b32 s49, 1
	s_branch .LBB0_457
